# wo GEMM: weight tile by LDS-DMA into swizzled double buffer (LDS 49184 B), activation tile register-staged two k-steps ahead; on top of v36
# speedup vs baseline: 1.0240x; 1.0038x over previous
;   DI u16* ob() const { return (u16*)(ws + OFF_ob); }
; #define tid_opaque() tid_from(WAVE_S)
;   const int tid = tid_opaque(), lane = tid & 63;
;   u16* Xs = lds;
;   u16* Ys = lds + 128 * LSTR;
;   const int lr = tid >> 3, lc = (tid & 7) * 8;
;   const u16* xg = X + (size_t)lr * RS + lc;
;   const u16* yg = Y + (size_t)lr * RS + lc;
;   u32x4 xr[4], yr[4];
; #pragma unroll
;   for (int it = 0; it < 4; ++it) {
;     xr[it] = *(const u32x4*)(xg + (size_t)it * 32 * RS);
;     yr[it] = *(const u32x4*)(yg + (size_t)it * 32 * RS);
;   }
; #pragma unroll
;   for (int a = 0; a < TI; ++a)
; #pragma unroll
;     for (int b = 0; b < TJ; ++b)
; #pragma unroll
;       for (int r = 0; r < 16; ++r) acc[a][b][r] = 0.f;
;   const int fr = lane & 31, fh = (lane >> 5) * 8;
;   for (int kt = 0; kt < NKT; ++kt) {
;     __syncthreads();
; #pragma unroll
;     for (int it = 0; it < 4; ++it) {
;       *(u32x4*)(Xs + (lr + 32 * it) * LSTR + lc) = xr[it];
;       *(u32x4*)(Ys + (lr + 32 * it) * LSTR + lc) = yr[it];
;     }
;     __syncthreads();
;     if (kt + 1 < NKT) {
; #pragma unroll
;       for (int it = 0; it < 4; ++it) {
;         xr[it] = *(const u32x4*)(xg + (size_t)it * 32 * RS + (kt + 1) * 64);
;         yr[it] = *(const u32x4*)(yg + (size_t)it * 32 * RS + (kt + 1) * 64);
;       }
;     }
; DI void phase_wo(const Params& p, int layer, u16* lds, const int WAVE_S) {
;     ...
;     const int slot = next_item(ctr, WAVE_S);
;     if (slot >= 512) break;
;     const int ft = slot & 7, tt = (slot >> 3) * 8 + xcd;
;     f32x16 acc[2][2];
;     gemm_tile<2, 2>(W + (size_t)ft * 128 * DM, p.ob() + (size_t)tt * 128 * DM, acc, lds, wi0, wj0, WAVE_S);
.LBB0_258:
	s_or_b64 exec, exec, s[18:19]
	s_waitcnt lgkmcnt(0)
	s_barrier
	ds_read_b32 v0, v1 offset:40976
	s_movk_i32 s18, 0x1ff
	s_waitcnt lgkmcnt(0)
	v_cmp_lt_i32_e32 vcc, s18, v0
	v_readfirstlane_b32 s28, v0
	s_mov_b64 s[18:19], -1
	s_cbranch_vccnz .LBB0_253
	s_and_b32 s18, s28, 7
	s_and_b32 s19, s28, -8
	s_or_b32 s40, s19, s17
	s_lshl_b32 s28, s18, 18
	v_mbcnt_lo_u32_b32 v14, -1, 0
	v_mbcnt_hi_u32_b32 v14, -1, v14
	s_add_u32 s44, s46, s28
	v_add_u32_e32 v0, s33, v14
	v_ashrrev_i32_e32 v2, 3, v0
	s_addc_u32 s45, s47, 0
	s_ashr_i32 s41, s40, 31
	v_ashrrev_i32_e32 v3, 31, v2
	s_lshl_b64 s[48:49], s[40:41], 18
	v_readlane_b32 s50, v165, 56
	v_lshlrev_b64 v[4:5], 11, v[2:3]
	v_lshlrev_b32_e32 v0, 4, v14
	v_readlane_b32 s51, v165, 57
	s_add_u32 s50, s50, s48
	v_lshl_add_u64 v[6:7], s[44:45], 0, v[4:5]
	v_and_b32_e32 v0, 0x70, v0
	s_addc_u32 s51, s51, s49
	s_mov_b32 s100, s44
	s_mov_b32 s101, s45
	v_or_b32_e32 v120, v4, v0
	v_add_u32_e32 v121, s81, v120
	v_add_u32_e32 v122, s12, v120
	v_add_u32_e32 v123, s86, v120
	v_bfe_u32 v119, v2, 1, 3
	v_lshlrev_b32_e32 v119, 4, v119
	v_xor_b32_e32 v119, v0, v119
	v_lshl_or_b32 v118, v2, 7, v119
	s_lshr_b32 s84, s33, 6
	s_lshr_b32 s32, s84, 1
	s_lshl_b32 s84, s84, 12
	s_lshl_b32 s28, s32, 5
	s_add_u32 s85, s84, 0x8000
	s_add_u32 s85, s85, s28
	v_lshrrev_b32_e32 v127, 3, v14
	s_lshr_b32 s28, s33, 1
	v_add_u32_e32 v127, s28, v127
	v_lshlrev_b32_e32 v127, 11, v127
	v_and_b32_e32 v144, 7, v14
	v_lshrrev_b32_e32 v145, 4, v14
	v_xor_b32_e32 v144, v144, v145
	v_lshl_add_u32 v90, v144, 4, v127
	v_xor_b32_e32 v144, 4, v144
	v_lshl_add_u32 v91, v144, 4, v127
	v_add_u32_e32 v91, 0x3c00, v91
	v_add_u32_e32 v92, 0x7800, v90
	v_add_u32_e32 v93, 0x7800, v91
	v_and_b32_e32 v156, 31, v14
	v_lshlrev_b32_e32 v156, 7, v156
	v_bfe_u32 v157, v14, 1, 3
	v_lshrrev_b32_e32 v158, 5, v14
	v_xor_b32_e32 v157, v157, v158
	v_xor_b32_e32 v159, 0, v157
	v_lshl_add_u32 v66, v159, 4, v156
	v_xor_b32_e32 v159, 2, v157
	v_lshl_add_u32 v67, v159, 4, v156
	v_xor_b32_e32 v159, 4, v157
	v_lshl_add_u32 v68, v159, 4, v156
	v_xor_b32_e32 v159, 6, v157
	v_lshl_add_u32 v69, v159, 4, v156
	s_lshl_b32 s28, s32, 13
	s_mul_i32 s32, s32, 0x2020
	s_add_u32 s32, s32, 0x8000
	s_and_b32 s19, s33, 64
	s_lshl_b32 s19, s19, 7
	s_add_u32 s19, s19, 0x4000
	v_add_u32_e32 v74, s32, v66
	v_add_u32_e32 v82, s19, v66
	v_add_u32_e32 v75, s32, v67
	v_add_u32_e32 v83, s19, v67
	v_add_u32_e32 v76, s32, v68
	v_add_u32_e32 v84, s19, v68
	v_add_u32_e32 v77, s32, v69
	v_add_u32_e32 v85, s19, v69
	v_add_u32_e32 v66, s28, v66
	v_add_u32_e32 v67, s28, v67
	v_add_u32_e32 v68, s28, v68
	v_add_u32_e32 v69, s28, v69
	v_lshl_add_u64 v[6:7], v[6:7], 0, v[0:1]
	v_lshl_add_u64 v[8:9], s[50:51], 0, v[4:5]
	v_add_co_u32_e32 v10, vcc, s81, v6
	v_lshl_add_u64 v[8:9], v[8:9], 0, v[0:1]
	s_nop 0
	v_addc_co_u32_e32 v11, vcc, 0, v7, vcc
	v_add_co_u32_e32 v12, vcc, s81, v8
	global_load_dwordx4 v[70:73], v120, s[50:51]
	global_load_dwordx4 v[78:81], v121, s[50:51]
	v_addc_co_u32_e32 v13, vcc, 0, v9, vcc
	global_load_dwordx4 v[86:89], v122, s[50:51]
	global_load_dwordx4 v[94:97], v123, s[50:51]
	v_add_co_u32_e32 v10, vcc, s12, v6
	v_and_b32_e32 v3, 31, v14
	s_nop 0
	v_addc_co_u32_e32 v11, vcc, 0, v7, vcc
	v_add_co_u32_e32 v12, vcc, s12, v8
	s_nop 0
	s_nop 0
	v_addc_co_u32_e32 v13, vcc, 0, v9, vcc
	v_add_co_u32_e32 v6, vcc, s86, v6
	s_mov_b32 m0, s84
	s_nop 0
	global_load_lds_dwordx4 v90, s[100:101]
	global_load_lds_dwordx4 v91, s[100:101] offset:1024
	v_addc_co_u32_e32 v7, vcc, 0, v7, vcc
	v_add_co_u32_e32 v8, vcc, s86, v8
	s_mov_b64 s[44:45], 0
	s_nop 0
	v_addc_co_u32_e32 v9, vcc, 0, v9, vcc
	global_load_lds_dwordx4 v92, s[100:101] offset:2048
	global_load_lds_dwordx4 v93, s[100:101] offset:3072
	global_load_dwordx4 v[102:105], v120, s[50:51] offset:128
	global_load_dwordx4 v[106:109], v121, s[50:51] offset:128
	global_load_dwordx4 v[110:113], v122, s[50:51] offset:128
	global_load_dwordx4 v[114:117], v123, s[50:51] offset:128
	v_or_b32_e32 v6, v3, v98
	v_or_b32_e32 v3, v3, v124
	v_mul_u32_u24_e32 v8, 0x90, v3
	v_lshl_add_u64 v[2:3], s[28:29], 0, v[4:5]
	v_or_b32_e32 v2, v2, v0
	s_nop 0
	v_lshl_add_u64 v[2:3], s[48:49], 0, v[4:5]
	v_lshrrev_b32_e32 v7, 1, v14
	v_or_b32_e32 v2, v2, v0
	v_and_b32_e32 v7, 16, v7
	v_mul_lo_u32 v6, v6, s13
	s_nop 0
	v_mov_b32_e32 v2, 0
	v_add_u32_e32 v101, v7, v6
	v_add_u32_e32 v0, v7, v8
	v_mov_b32_e32 v3, v2
	v_mov_b32_e32 v4, v2
	v_mov_b32_e32 v5, v2
	v_mov_b32_e32 v6, v2
	v_mov_b32_e32 v7, v2
	v_mov_b32_e32 v8, v2
	v_mov_b32_e32 v9, v2
	v_mov_b32_e32 v10, v2
	v_mov_b32_e32 v11, v2
	v_mov_b32_e32 v12, v2
	v_mov_b32_e32 v13, v2
	v_mov_b32_e32 v14, v2
	v_mov_b32_e32 v15, v2
	v_mov_b32_e32 v16, v2
	v_mov_b32_e32 v17, v2
	v_mov_b32_e32 v34, v2
	v_mov_b32_e32 v35, v2
	v_mov_b32_e32 v36, v2
	v_mov_b32_e32 v37, v2
	s_waitcnt vmcnt(8)
	v_mov_b32_e32 v38, v2
	v_mov_b32_e32 v39, v2
	v_mov_b32_e32 v40, v2
	v_mov_b32_e32 v41, v2
	v_mov_b32_e32 v42, v2
	v_mov_b32_e32 v43, v2
	v_mov_b32_e32 v44, v2
	v_mov_b32_e32 v45, v2
	s_waitcnt vmcnt(10)
	v_mov_b32_e32 v46, v2
	v_mov_b32_e32 v47, v2
	v_mov_b32_e32 v48, v2
	v_mov_b32_e32 v49, v2
	v_mov_b32_e32 v18, v2
	v_mov_b32_e32 v19, v2
	v_mov_b32_e32 v20, v2
	v_mov_b32_e32 v21, v2
	v_mov_b32_e32 v22, v2
	v_mov_b32_e32 v23, v2
	v_mov_b32_e32 v24, v2
	v_mov_b32_e32 v25, v2
	v_mov_b32_e32 v26, v2
	v_mov_b32_e32 v27, v2
	v_mov_b32_e32 v28, v2
	v_mov_b32_e32 v29, v2
	v_mov_b32_e32 v30, v2
	v_mov_b32_e32 v31, v2
	v_mov_b32_e32 v32, v2
	v_mov_b32_e32 v33, v2
	v_mov_b32_e32 v50, v2
	v_mov_b32_e32 v51, v2
	v_mov_b32_e32 v52, v2
	v_mov_b32_e32 v53, v2
	s_waitcnt vmcnt(8)
	v_mov_b32_e32 v54, v2
	v_mov_b32_e32 v55, v2
	v_mov_b32_e32 v56, v2
	v_mov_b32_e32 v57, v2
	v_mov_b32_e32 v58, v2
	v_mov_b32_e32 v59, v2
	v_mov_b32_e32 v60, v2
	v_mov_b32_e32 v61, v2
	v_mov_b32_e32 v62, v2
	v_mov_b32_e32 v63, v2
	v_mov_b32_e32 v64, v2
	v_mov_b32_e32 v65, v2
	s_movk_i32 s98, 7
; #define MFMA32(a, b, c) __builtin_amdgcn_mfma_f32_32x32x16_bf16((a), (b), (c), 0, 0, 0)
;     ...
;   for (int kt = 0; kt < NKT; ++kt) {
;     __syncthreads();
; #pragma unroll
;     for (int it = 0; it < 4; ++it) {
;       *(u32x4*)(Xs + (lr + 32 * it) * LSTR + lc) = xr[it];
;       *(u32x4*)(Ys + (lr + 32 * it) * LSTR + lc) = yr[it];
;     }
;     __syncthreads();
;     if (kt + 1 < NKT) {
; #pragma unroll
;       for (int it = 0; it < 4; ++it) {
;         xr[it] = *(const u32x4*)(xg + (size_t)it * 32 * RS + (kt + 1) * 64);
;         yr[it] = *(const u32x4*)(yg + (size_t)it * 32 * RS + (kt + 1) * 64);
;       }
;     }
; #pragma unroll
;     for (int ks = 0; ks < 4; ++ks) {
;       bf16x8 af[TI], bfr[TJ];
; #pragma unroll
;       for (int a = 0; a < TI; ++a) af[a] = *(const bf16x8*)(Xs + (wi0 + a * 32 + fr) * LSTR + ks * 16 + fh);
; #pragma unroll
;       for (int b = 0; b < TJ; ++b) bfr[b] = *(const bf16x8*)(Ys + (wj0 + b * 32 + fr) * LSTR + ks * 16 + fh);
; #pragma unroll
;       for (int a = 0; a < TI; ++a)
; #pragma unroll
;         for (int b = 0; b < TJ; ++b) acc[a][b] = MFMA32(af[a], bfr[b], acc[a][b]);
;     }
;     __builtin_amdgcn_iglp_opt(1);
;   }
.Lwd_k:
	s_barrier
	s_waitcnt vmcnt(11)
	ds_write_b128 v118, v[70:73] offset:16384
	s_waitcnt vmcnt(10)
	ds_write_b128 v118, v[78:81] offset:20480
	s_waitcnt vmcnt(9)
	ds_write_b128 v118, v[86:89] offset:24576
	s_waitcnt vmcnt(8)
	ds_write_b128 v118, v[94:97] offset:28672
	s_waitcnt vmcnt(4)
	s_add_u32 s100, s100, 0x80
	s_addc_u32 s101, s101, 0
	s_mov_b32 m0, s85
	s_nop 0
	global_load_lds_dwordx4 v90, s[100:101]
	global_load_lds_dwordx4 v91, s[100:101] offset:1024
	global_load_lds_dwordx4 v92, s[100:101] offset:2048
	global_load_lds_dwordx4 v93, s[100:101] offset:3072
	s_waitcnt lgkmcnt(0)
	s_barrier
	ds_read_b128 v[128:131], v66 offset:4096
	ds_read_b128 v[136:139], v66
	ds_read_b128 v[132:135], v82 offset:4096
	ds_read_b128 v[148:151], v82
	ds_read_b128 v[140:143], v67
	ds_read_b128 v[152:155], v83
	s_waitcnt lgkmcnt(2)
	v_mfma_f32_32x32x16_bf16 v[34:49], v[128:131], v[148:151], v[34:49]
	v_mfma_f32_32x32x16_bf16 v[2:17], v[128:131], v[132:135], v[2:17]
	ds_read_b128 v[128:131], v67 offset:4096
	v_mfma_f32_32x32x16_bf16 v[18:33], v[136:139], v[132:135], v[18:33]
	ds_read_b128 v[132:135], v83 offset:4096
	s_waitcnt lgkmcnt(1)
	v_mfma_f32_32x32x16_bf16 v[34:49], v[128:131], v[152:155], v[34:49]
	s_waitcnt lgkmcnt(0)
	v_mfma_f32_32x32x16_bf16 v[2:17], v[128:131], v[132:135], v[2:17]
	ds_read_b128 v[128:131], v68
	v_mfma_f32_32x32x16_bf16 v[18:33], v[140:143], v[132:135], v[18:33]
	ds_read_b128 v[132:135], v68 offset:4096
	v_mfma_f32_32x32x16_bf16 v[50:65], v[136:139], v[148:151], v[50:65]
	ds_read_b128 v[136:139], v84
	v_mfma_f32_32x32x16_bf16 v[50:65], v[140:143], v[152:155], v[50:65]
	ds_read_b128 v[140:143], v84 offset:4096
	s_waitcnt lgkmcnt(1)
	v_mfma_f32_32x32x16_bf16 v[50:65], v[128:131], v[136:139], v[50:65]
	s_waitcnt lgkmcnt(0)
	v_mfma_f32_32x32x16_bf16 v[18:33], v[128:131], v[140:143], v[18:33]
	ds_read_b128 v[128:131], v69
	v_mfma_f32_32x32x16_bf16 v[34:49], v[132:135], v[136:139], v[34:49]
	v_mfma_f32_32x32x16_bf16 v[2:17], v[132:135], v[140:143], v[2:17]
	ds_read_b128 v[132:135], v69 offset:4096
	ds_read_b128 v[136:139], v85
	ds_read_b128 v[140:143], v85 offset:4096
	s_add_u32 s50, s50, 0x80
	s_addc_u32 s51, s51, 0
	global_load_dwordx4 v[70:73], v120, s[50:51] offset:128
	global_load_dwordx4 v[78:81], v121, s[50:51] offset:128
	global_load_dwordx4 v[86:89], v122, s[50:51] offset:128
	global_load_dwordx4 v[94:97], v123, s[50:51] offset:128
	s_waitcnt lgkmcnt(1)
	v_mfma_f32_32x32x16_bf16 v[50:65], v[128:131], v[136:139], v[50:65]
	s_waitcnt lgkmcnt(0)
	v_mfma_f32_32x32x16_bf16 v[18:33], v[128:131], v[140:143], v[18:33]
	v_mfma_f32_32x32x16_bf16 v[34:49], v[132:135], v[136:139], v[34:49]
	v_mfma_f32_32x32x16_bf16 v[2:17], v[132:135], v[140:143], v[2:17]
	s_barrier
	s_waitcnt vmcnt(11)
	ds_write_b128 v118, v[102:105] offset:16384
	s_waitcnt vmcnt(10)
	ds_write_b128 v118, v[106:109] offset:20480
	s_waitcnt vmcnt(9)
	ds_write_b128 v118, v[110:113] offset:24576
	s_waitcnt vmcnt(8)
	ds_write_b128 v118, v[114:117] offset:28672
	s_waitcnt vmcnt(4)
	s_add_u32 s100, s100, 0x80
	s_addc_u32 s101, s101, 0
	s_mov_b32 m0, s84
	s_nop 0
	global_load_lds_dwordx4 v90, s[100:101]
	global_load_lds_dwordx4 v91, s[100:101] offset:1024
	global_load_lds_dwordx4 v92, s[100:101] offset:2048
	global_load_lds_dwordx4 v93, s[100:101] offset:3072
	s_waitcnt lgkmcnt(0)
	s_barrier
	ds_read_b128 v[128:131], v74 offset:4096
	ds_read_b128 v[136:139], v74
	ds_read_b128 v[132:135], v82 offset:4096
	ds_read_b128 v[148:151], v82
	ds_read_b128 v[140:143], v75
	ds_read_b128 v[152:155], v83
	s_waitcnt lgkmcnt(2)
	v_mfma_f32_32x32x16_bf16 v[34:49], v[128:131], v[148:151], v[34:49]
	v_mfma_f32_32x32x16_bf16 v[2:17], v[128:131], v[132:135], v[2:17]
	ds_read_b128 v[128:131], v75 offset:4096
	v_mfma_f32_32x32x16_bf16 v[18:33], v[136:139], v[132:135], v[18:33]
	ds_read_b128 v[132:135], v83 offset:4096
	s_waitcnt lgkmcnt(1)
	v_mfma_f32_32x32x16_bf16 v[34:49], v[128:131], v[152:155], v[34:49]
	s_waitcnt lgkmcnt(0)
	v_mfma_f32_32x32x16_bf16 v[2:17], v[128:131], v[132:135], v[2:17]
	ds_read_b128 v[128:131], v76
	v_mfma_f32_32x32x16_bf16 v[18:33], v[140:143], v[132:135], v[18:33]
	ds_read_b128 v[132:135], v76 offset:4096
	v_mfma_f32_32x32x16_bf16 v[50:65], v[136:139], v[148:151], v[50:65]
	ds_read_b128 v[136:139], v84
	v_mfma_f32_32x32x16_bf16 v[50:65], v[140:143], v[152:155], v[50:65]
	ds_read_b128 v[140:143], v84 offset:4096
	s_waitcnt lgkmcnt(1)
	v_mfma_f32_32x32x16_bf16 v[50:65], v[128:131], v[136:139], v[50:65]
	s_waitcnt lgkmcnt(0)
	v_mfma_f32_32x32x16_bf16 v[18:33], v[128:131], v[140:143], v[18:33]
	ds_read_b128 v[128:131], v77
	v_mfma_f32_32x32x16_bf16 v[34:49], v[132:135], v[136:139], v[34:49]
	v_mfma_f32_32x32x16_bf16 v[2:17], v[132:135], v[140:143], v[2:17]
	ds_read_b128 v[132:135], v77 offset:4096
	ds_read_b128 v[136:139], v85
	ds_read_b128 v[140:143], v85 offset:4096
	s_add_u32 s50, s50, 0x80
	s_addc_u32 s51, s51, 0
	global_load_dwordx4 v[102:105], v120, s[50:51] offset:128
	global_load_dwordx4 v[106:109], v121, s[50:51] offset:128
	global_load_dwordx4 v[110:113], v122, s[50:51] offset:128
	global_load_dwordx4 v[114:117], v123, s[50:51] offset:128
	s_waitcnt lgkmcnt(1)
	v_mfma_f32_32x32x16_bf16 v[50:65], v[128:131], v[136:139], v[50:65]
	s_waitcnt lgkmcnt(0)
	v_mfma_f32_32x32x16_bf16 v[18:33], v[128:131], v[140:143], v[18:33]
	v_mfma_f32_32x32x16_bf16 v[34:49], v[132:135], v[136:139], v[34:49]
	v_mfma_f32_32x32x16_bf16 v[2:17], v[132:135], v[140:143], v[2:17]
	s_sub_u32 s98, s98, 1
	s_cmp_lg_u32 s98, 0
	s_cbranch_scc1 .Lwd_k
	s_barrier
; #define MFMA32(a, b, c) __builtin_amdgcn_mfma_f32_32x32x16_bf16((a), (b), (c), 0, 0, 0)
;     ...
;   for (int kt = 0; kt < NKT; ++kt) {
;     __syncthreads();
; #pragma unroll
;     for (int it = 0; it < 4; ++it) {
;       *(u32x4*)(Xs + (lr + 32 * it) * LSTR + lc) = xr[it];
;       *(u32x4*)(Ys + (lr + 32 * it) * LSTR + lc) = yr[it];
;     }
;     __syncthreads();
;     if (kt + 1 < NKT) {
; #pragma unroll
;       for (int it = 0; it < 4; ++it) {
;         xr[it] = *(const u32x4*)(xg + (size_t)it * 32 * RS + (kt + 1) * 64);
;         yr[it] = *(const u32x4*)(yg + (size_t)it * 32 * RS + (kt + 1) * 64);
;       }
;     }
; #pragma unroll
;     for (int ks = 0; ks < 4; ++ks) {
;       bf16x8 af[TI], bfr[TJ];
; #pragma unroll
;       for (int a = 0; a < TI; ++a) af[a] = *(const bf16x8*)(Xs + (wi0 + a * 32 + fr) * LSTR + ks * 16 + fh);
; #pragma unroll
;       for (int b = 0; b < TJ; ++b) bfr[b] = *(const bf16x8*)(Ys + (wj0 + b * 32 + fr) * LSTR + ks * 16 + fh);
; #pragma unroll
;       for (int a = 0; a < TI; ++a)
; #pragma unroll
;         for (int b = 0; b < TJ; ++b) acc[a][b] = MFMA32(af[a], bfr[b], acc[a][b]);
;     }
;     __builtin_amdgcn_iglp_opt(1);
;   }
	s_waitcnt vmcnt(11)
	ds_write_b128 v118, v[70:73] offset:16384
	s_waitcnt vmcnt(10)
	ds_write_b128 v118, v[78:81] offset:20480
	s_waitcnt vmcnt(9)
	ds_write_b128 v118, v[86:89] offset:24576
	s_waitcnt vmcnt(8)
	ds_write_b128 v118, v[94:97] offset:28672
	s_waitcnt vmcnt(4)
	s_add_u32 s100, s100, 0x80
	s_addc_u32 s101, s101, 0
	s_mov_b32 m0, s85
	s_nop 0
	global_load_lds_dwordx4 v90, s[100:101]
	global_load_lds_dwordx4 v91, s[100:101] offset:1024
	global_load_lds_dwordx4 v92, s[100:101] offset:2048
	global_load_lds_dwordx4 v93, s[100:101] offset:3072
	s_waitcnt lgkmcnt(0)
	s_barrier
	ds_read_b128 v[128:131], v66 offset:4096
	ds_read_b128 v[136:139], v66
	ds_read_b128 v[132:135], v82 offset:4096
	ds_read_b128 v[148:151], v82
	ds_read_b128 v[140:143], v67
	ds_read_b128 v[152:155], v83
	s_waitcnt lgkmcnt(2)
	v_mfma_f32_32x32x16_bf16 v[34:49], v[128:131], v[148:151], v[34:49]
	v_mfma_f32_32x32x16_bf16 v[2:17], v[128:131], v[132:135], v[2:17]
	ds_read_b128 v[128:131], v67 offset:4096
	v_mfma_f32_32x32x16_bf16 v[18:33], v[136:139], v[132:135], v[18:33]
	ds_read_b128 v[132:135], v83 offset:4096
	s_waitcnt lgkmcnt(1)
	v_mfma_f32_32x32x16_bf16 v[34:49], v[128:131], v[152:155], v[34:49]
	s_waitcnt lgkmcnt(0)
	v_mfma_f32_32x32x16_bf16 v[2:17], v[128:131], v[132:135], v[2:17]
	ds_read_b128 v[128:131], v68
	v_mfma_f32_32x32x16_bf16 v[18:33], v[140:143], v[132:135], v[18:33]
	ds_read_b128 v[132:135], v68 offset:4096
	v_mfma_f32_32x32x16_bf16 v[50:65], v[136:139], v[148:151], v[50:65]
	ds_read_b128 v[136:139], v84
	v_mfma_f32_32x32x16_bf16 v[50:65], v[140:143], v[152:155], v[50:65]
	ds_read_b128 v[140:143], v84 offset:4096
	s_waitcnt lgkmcnt(1)
	v_mfma_f32_32x32x16_bf16 v[50:65], v[128:131], v[136:139], v[50:65]
	s_waitcnt lgkmcnt(0)
	v_mfma_f32_32x32x16_bf16 v[18:33], v[128:131], v[140:143], v[18:33]
	ds_read_b128 v[128:131], v69
	v_mfma_f32_32x32x16_bf16 v[34:49], v[132:135], v[136:139], v[34:49]
	v_mfma_f32_32x32x16_bf16 v[2:17], v[132:135], v[140:143], v[2:17]
	ds_read_b128 v[132:135], v69 offset:4096
	ds_read_b128 v[136:139], v85
	ds_read_b128 v[140:143], v85 offset:4096
	s_waitcnt lgkmcnt(1)
	v_mfma_f32_32x32x16_bf16 v[50:65], v[128:131], v[136:139], v[50:65]
	s_waitcnt lgkmcnt(0)
	v_mfma_f32_32x32x16_bf16 v[18:33], v[128:131], v[140:143], v[18:33]
	v_mfma_f32_32x32x16_bf16 v[34:49], v[132:135], v[136:139], v[34:49]
	v_mfma_f32_32x32x16_bf16 v[2:17], v[132:135], v[140:143], v[2:17]
	s_barrier
	s_waitcnt vmcnt(7)
	ds_write_b128 v118, v[102:105] offset:16384
	s_waitcnt vmcnt(6)
	ds_write_b128 v118, v[106:109] offset:20480
	s_waitcnt vmcnt(5)
	ds_write_b128 v118, v[110:113] offset:24576
	s_waitcnt vmcnt(4)
	ds_write_b128 v118, v[114:117] offset:28672
	s_waitcnt vmcnt(0)
	s_waitcnt lgkmcnt(0)
	s_barrier
	ds_read_b128 v[128:131], v74 offset:4096
	ds_read_b128 v[136:139], v74
	ds_read_b128 v[132:135], v82 offset:4096
	ds_read_b128 v[148:151], v82
	ds_read_b128 v[140:143], v75
	ds_read_b128 v[152:155], v83
	s_waitcnt lgkmcnt(2)
	v_mfma_f32_32x32x16_bf16 v[34:49], v[128:131], v[148:151], v[34:49]
	v_mfma_f32_32x32x16_bf16 v[2:17], v[128:131], v[132:135], v[2:17]
	ds_read_b128 v[128:131], v75 offset:4096
	v_mfma_f32_32x32x16_bf16 v[18:33], v[136:139], v[132:135], v[18:33]
	ds_read_b128 v[132:135], v83 offset:4096
	s_waitcnt lgkmcnt(1)
	v_mfma_f32_32x32x16_bf16 v[34:49], v[128:131], v[152:155], v[34:49]
	s_waitcnt lgkmcnt(0)
	v_mfma_f32_32x32x16_bf16 v[2:17], v[128:131], v[132:135], v[2:17]
	ds_read_b128 v[128:131], v76
	v_mfma_f32_32x32x16_bf16 v[18:33], v[140:143], v[132:135], v[18:33]
	ds_read_b128 v[132:135], v76 offset:4096
	v_mfma_f32_32x32x16_bf16 v[50:65], v[136:139], v[148:151], v[50:65]
	ds_read_b128 v[136:139], v84
	v_mfma_f32_32x32x16_bf16 v[50:65], v[140:143], v[152:155], v[50:65]
	ds_read_b128 v[140:143], v84 offset:4096
	s_waitcnt lgkmcnt(1)
	v_mfma_f32_32x32x16_bf16 v[50:65], v[128:131], v[136:139], v[50:65]
	s_waitcnt lgkmcnt(0)
	v_mfma_f32_32x32x16_bf16 v[18:33], v[128:131], v[140:143], v[18:33]
	ds_read_b128 v[128:131], v77
	v_mfma_f32_32x32x16_bf16 v[34:49], v[132:135], v[136:139], v[34:49]
	v_mfma_f32_32x32x16_bf16 v[2:17], v[132:135], v[140:143], v[2:17]
	ds_read_b128 v[132:135], v77 offset:4096
	ds_read_b128 v[136:139], v85
	ds_read_b128 v[140:143], v85 offset:4096
	s_waitcnt lgkmcnt(1)
	v_mfma_f32_32x32x16_bf16 v[50:65], v[128:131], v[136:139], v[50:65]
	s_waitcnt lgkmcnt(0)
	v_mfma_f32_32x32x16_bf16 v[18:33], v[128:131], v[140:143], v[18:33]
	v_mfma_f32_32x32x16_bf16 v[34:49], v[132:135], v[136:139], v[34:49]
	v_mfma_f32_32x32x16_bf16 v[2:17], v[132:135], v[140:143], v[2:17]
	s_waitcnt lgkmcnt(0)
	s_barrier
;   DI u16* yb() const { return (u16*)(ws + OFF_yb); }
; DI void phase_wo(const Params& p, int layer, u16* lds, const int WAVE_S) {
;     ...
;     __syncthreads();
;     u16* wl = lds + wave * 64 * LSTR;
; #pragma unroll
;     for (int tj = 0; tj < 2; ++tj)
; #pragma unroll
;       for (int ti = 0; ti < 2; ++ti)
; #pragma unroll
;         for (int g4 = 0; g4 < 4; ++g4)
;           *(uint2*)(wl + (tj * 32 + r) * LSTR + ti * 32 + 8 * g4 + 4 * h) =
;               make_uint2(pk2(acc[ti][tj][4 * g4 + 0], acc[ti][tj][4 * g4 + 1]), pk2(acc[ti][tj][4 * g4 + 2], acc[ti][tj][4 * g4 + 3]));
;     u16* dst = p.yb() + (size_t)(tt * 128 + wj0) * DM + ft * 128 + wi0;
; #pragma unroll
;     for (int it = 0; it < 8; ++it) {
;       const int row = it * 8 + (lane >> 3), ch = lane & 7;
;       *(u32x4*)(dst + (size_t)row * DM + ch * 8) = *(const u32x4*)(wl + row * LSTR + ch * 8);
;     }
	s_nop 7
	s_nop 7
	v_mbcnt_lo_u32_b32 v119, -1, 0
	v_mbcnt_hi_u32_b32 v119, -1, v119
	v_bfe_u32 v119, v119, 3, 3
	v_lshlrev_b32_e32 v102, 11, v119
	v_or_b32_e32 v104, 0x4000, v102
	v_or_b32_e32 v106, 0x8000, v102
	v_or_b32_e32 v108, 0xc000, v102
	v_or_b32_e32 v110, 0x10000, v102
	v_or_b32_e32 v112, 0x14000, v102
	v_or_b32_e32 v114, 0x18000, v102
	v_or_b32_e32 v116, 0x1c000, v102
	s_lshl_b32 s28, s18, 8
	v_mov_b32_e32 v103, v1
	v_mov_b32_e32 v105, v1
	v_mov_b32_e32 v107, v1
	v_mov_b32_e32 v109, v1
	v_mov_b32_e32 v111, v1
	v_mov_b32_e32 v113, v1
	v_mov_b32_e32 v115, v1
	v_mov_b32_e32 v117, v1
	s_mov_b64 s[18:19], 0
	s_movk_i32 s50, 0x6000
	v_add_u32_e32 v0, 0x1000, v125
	v_mov_b32_e32 v101, v1
	v_cvt_pk_bf16_f32 v50, v50, v51
	v_cvt_pk_bf16_f32 v51, v52, v53
	v_cvt_pk_bf16_f32 v52, v54, v55
	v_cvt_pk_bf16_f32 v53, v56, v57
	ds_write2_b64 v125, v[50:51], v[52:53] offset1:2
	v_cvt_pk_bf16_f32 v50, v58, v59
	v_cvt_pk_bf16_f32 v51, v60, v61
	v_cvt_pk_bf16_f32 v52, v62, v63
	v_cvt_pk_bf16_f32 v53, v64, v65
	ds_write2_b64 v125, v[50:51], v[52:53] offset0:4 offset1:6
	v_cvt_pk_bf16_f32 v18, v18, v19
	v_cvt_pk_bf16_f32 v19, v20, v21
	v_cvt_pk_bf16_f32 v20, v22, v23
	v_cvt_pk_bf16_f32 v21, v24, v25
	v_cvt_pk_bf16_f32 v34, v34, v35
	v_cvt_pk_bf16_f32 v35, v36, v37
	v_cvt_pk_bf16_f32 v36, v38, v39
	v_cvt_pk_bf16_f32 v37, v40, v41
	ds_write2_b64 v125, v[34:35], v[36:37] offset0:8 offset1:10
	v_cvt_pk_bf16_f32 v34, v42, v43
	v_cvt_pk_bf16_f32 v35, v44, v45
	v_cvt_pk_bf16_f32 v36, v46, v47
	v_cvt_pk_bf16_f32 v37, v48, v49
	ds_write2_b64 v125, v[34:35], v[36:37] offset0:12 offset1:14
	ds_write2_b64 v0, v[18:19], v[20:21] offset0:64 offset1:66
	v_cvt_pk_bf16_f32 v18, v26, v27
	v_cvt_pk_bf16_f32 v19, v28, v29
	v_cvt_pk_bf16_f32 v20, v30, v31
	v_cvt_pk_bf16_f32 v21, v32, v33
	s_nop 1
	v_cvt_pk_bf16_f32 v2, v2, v3
	v_cvt_pk_bf16_f32 v3, v4, v5
	v_cvt_pk_bf16_f32 v4, v6, v7
	v_cvt_pk_bf16_f32 v5, v8, v9
	ds_write2_b64 v0, v[18:19], v[20:21] offset0:68 offset1:70
	ds_write2_b64 v0, v[2:3], v[4:5] offset0:72 offset1:74
	v_cvt_pk_bf16_f32 v2, v10, v11
	v_cvt_pk_bf16_f32 v3, v12, v13
	v_cvt_pk_bf16_f32 v4, v14, v15
	v_cvt_pk_bf16_f32 v5, v16, v17
	ds_write2_b64 v0, v[2:3], v[4:5] offset0:76 offset1:78
	v_lshl_or_b32 v2, s40, 7, v124
	v_ashrrev_i32_e32 v3, 31, v2
	v_readlane_b32 s40, v165, 58
	v_lshlrev_b64 v[2:3], 11, v[2:3]
	v_readlane_b32 s41, v165, 59
	s_nop 1
	v_lshl_add_u64 v[2:3], s[40:41], 0, v[2:3]
	v_lshl_add_u64 v[2:3], v[2:3], 0, s[28:29]
	v_lshl_add_u64 v[2:3], v[98:99], 1, v[2:3]
	v_lshl_add_u64 v[6:7], v[2:3], 0, v[100:101]
	ds_read_b128 v[2:5], v126
	v_lshl_add_u64 v[8:9], v[6:7], 0, v[102:103]
	s_waitcnt lgkmcnt(0)
	global_store_dwordx4 v[8:9], v[2:5], off nt
	ds_read_b128 v[2:5], v126 offset:1152
	v_lshl_add_u64 v[8:9], v[6:7], 0, v[104:105]
	s_waitcnt lgkmcnt(0)
	global_store_dwordx4 v[8:9], v[2:5], off nt
	ds_read_b128 v[2:5], v126 offset:2304
	v_lshl_add_u64 v[8:9], v[6:7], 0, v[106:107]
	s_waitcnt lgkmcnt(0)
	global_store_dwordx4 v[8:9], v[2:5], off nt
	ds_read_b128 v[2:5], v126 offset:3456
	v_lshl_add_u64 v[8:9], v[6:7], 0, v[108:109]
	s_waitcnt lgkmcnt(0)
	global_store_dwordx4 v[8:9], v[2:5], off nt
	ds_read_b128 v[2:5], v126 offset:4608
	v_lshl_add_u64 v[8:9], v[6:7], 0, v[110:111]
	s_waitcnt lgkmcnt(0)
	global_store_dwordx4 v[8:9], v[2:5], off nt
	ds_read_b128 v[2:5], v126 offset:5760
	v_lshl_add_u64 v[8:9], v[6:7], 0, v[112:113]
	s_waitcnt lgkmcnt(0)
	global_store_dwordx4 v[8:9], v[2:5], off nt
	ds_read_b128 v[2:5], v126 offset:6912
	v_lshl_add_u64 v[8:9], v[6:7], 0, v[114:115]
	v_lshl_add_u64 v[6:7], v[6:7], 0, v[116:117]
	s_waitcnt lgkmcnt(0)
	global_store_dwordx4 v[8:9], v[2:5], off nt
	ds_read_b128 v[2:5], v126 offset:8064
	s_waitcnt lgkmcnt(0)
	global_store_dwordx4 v[6:7], v[2:5], off nt
	s_branch .LBB0_253

; __global__ void __launch_bounds__(256, 3) mega_kernel(Params p) {
;   __shared__ __attribute__((aligned(16))) char lds[40960];
	.amdhsa_kernel _Z11mega_kernel6Params
		.amdhsa_group_segment_fixed_size 49184
		.amdhsa_private_segment_fixed_size 0
		.amdhsa_kernarg_size 416
		.amdhsa_user_sgpr_count 2
		.amdhsa_user_sgpr_dispatch_ptr 0
		.amdhsa_user_sgpr_queue_ptr 0
		.amdhsa_user_sgpr_kernarg_segment_ptr 1
		.amdhsa_user_sgpr_dispatch_id 0
		.amdhsa_user_sgpr_kernarg_preload_length 0
		.amdhsa_user_sgpr_kernarg_preload_offset 0
		.amdhsa_user_sgpr_private_segment_size 0
		.amdhsa_uses_dynamic_stack 0
		.amdhsa_enable_private_segment 0
		.amdhsa_system_sgpr_workgroup_id_x 1
		.amdhsa_system_sgpr_workgroup_id_y 0
		.amdhsa_system_sgpr_workgroup_id_z 0
		.amdhsa_system_sgpr_workgroup_info 0
		.amdhsa_system_vgpr_workitem_id 2
		.amdhsa_next_free_vgpr 168
		.amdhsa_next_free_sgpr 102
		.amdhsa_accum_offset 168
		.amdhsa_reserve_vcc 1
		.amdhsa_float_round_mode_32 0
		.amdhsa_float_round_mode_16_64 0
		.amdhsa_float_denorm_mode_32 3
		.amdhsa_float_denorm_mode_16_64 3
		.amdhsa_dx10_clamp 1
		.amdhsa_ieee_mode 1
		.amdhsa_fp16_overflow 0
		.amdhsa_tg_split 0
		.amdhsa_exception_fp_ieee_invalid_op 0
		.amdhsa_exception_fp_denorm_src 0
		.amdhsa_exception_fp_ieee_div_zero 0
		.amdhsa_exception_fp_ieee_overflow 0
		.amdhsa_exception_fp_ieee_underflow 0
		.amdhsa_exception_fp_ieee_inexact 0
		.amdhsa_exception_int_div_zero 0
	.end_amdhsa_kernel

; __global__ void __launch_bounds__(256, 3) mega_kernel(Params p) {
;   __shared__ __attribute__((aligned(16))) char lds[40960];
amdhsa.kernels:
  - .agpr_count:     0
    .args:
      - .offset:         0
        .size:           160
        .value_kind:     by_value
      - .offset:         160
        .size:           4
        .value_kind:     hidden_block_count_x
      - .offset:         164
        .size:           4
        .value_kind:     hidden_block_count_y
      - .offset:         168
        .size:           4
        .value_kind:     hidden_block_count_z
      - .offset:         172
        .size:           2
        .value_kind:     hidden_group_size_x
      - .offset:         174
        .size:           2
        .value_kind:     hidden_group_size_y
      - .offset:         176
        .size:           2
        .value_kind:     hidden_group_size_z
      - .offset:         178
        .size:           2
        .value_kind:     hidden_remainder_x
      - .offset:         180
        .size:           2
        .value_kind:     hidden_remainder_y
      - .offset:         182
        .size:           2
        .value_kind:     hidden_remainder_z
      - .offset:         200
        .size:           8
        .value_kind:     hidden_global_offset_x
      - .offset:         208
        .size:           8
        .value_kind:     hidden_global_offset_y
      - .offset:         216
        .size:           8
        .value_kind:     hidden_global_offset_z
      - .offset:         224
        .size:           2
        .value_kind:     hidden_grid_dims
      - .offset:         248
        .size:           8
        .value_kind:     hidden_multigrid_sync_arg
    .group_segment_fixed_size: 49184
    .kernarg_segment_align: 8
    .kernarg_segment_size: 416
    .language:       OpenCL C
    .language_version:
      - 2
      - 0
    .max_flat_workgroup_size: 256
    .name:           _Z11mega_kernel6Params
    .private_segment_fixed_size: 0
    .sgpr_count:     108
    .sgpr_spill_count: 205
    .symbol:         _Z11mega_kernel6Params.kd
    .uniform_work_group_size: 1
    .uses_dynamic_stack: false
    .vgpr_count:     168
    .vgpr_spill_count: 0
    .wavefront_size: 64
